# P0 ada GEMV: silu fill and 16 weight loads no longer serialized (hand-unrolled K loop)
# speedup vs baseline: 1.0476x; 1.0085x over previous
.LBB0_50:
	s_andn2_saveexec_b64 s[10:11], s[36:37]
	s_cbranch_execz .LBB0_9
	v_readlane_b32 s16, v245, 32
	s_mov_b64 s[4:5], 0
	v_readlane_b32 s24, v245, 40
	v_readlane_b32 s25, v245, 41
	v_readlane_b32 s30, v245, 46
	v_readlane_b32 s31, v245, 47
	v_readlane_b32 s17, v245, 33
	v_readlane_b32 s18, v245, 34
	v_readlane_b32 s19, v245, 35
	v_readlane_b32 s20, v245, 36
	v_readlane_b32 s21, v245, 37
	v_readlane_b32 s22, v245, 38
	v_readlane_b32 s23, v245, 39
	v_readlane_b32 s26, v245, 42
	v_readlane_b32 s27, v245, 43
	v_readlane_b32 s28, v245, 44
	v_readlane_b32 s29, v245, 45
	global_load_dword v170, v[36:37], off
	global_load_dword v171, v[36:37], off offset:1024
	global_load_dword v172, v[36:37], off offset:2048
	global_load_dword v173, v[38:39], off
	v_and_b32_e32 v168, 0xff, v212
	v_lshlrev_b32_e32 v168, 2, v168
	global_load_dword v174, v168, s[24:25]
	global_load_dword v175, v168, s[24:25] offset:1024
	global_load_dword v176, v168, s[24:25] offset:2048
	global_load_dword v177, v168, s[24:25] offset:3072
	v_add_u32_e32 v168, 0x1000, v168
	global_load_dword v178, v168, s[24:25]
	global_load_dword v179, v168, s[24:25] offset:1024
	global_load_dword v180, v168, s[24:25] offset:2048
	global_load_dword v181, v168, s[24:25] offset:3072
	v_add_u32_e32 v168, 0x1000, v168
	global_load_dword v182, v168, s[24:25]
	global_load_dword v183, v168, s[24:25] offset:1024
	global_load_dword v184, v168, s[24:25] offset:2048
	global_load_dword v185, v168, s[24:25] offset:3072
	v_add_u32_e32 v168, 0x1000, v168
	global_load_dword v186, v168, s[24:25]
	global_load_dword v187, v168, s[24:25] offset:1024
	global_load_dword v188, v168, s[24:25] offset:2048
	global_load_dword v189, v168, s[24:25] offset:3072
	s_waitcnt vmcnt(0)
	v_mul_f32_e32 v190, 0xbfb8aa3b, v170
	v_mul_f32_e32 v191, 0xbfb8aa3b, v171
	v_mul_f32_e32 v192, 0xbfb8aa3b, v172
	v_mul_f32_e32 v193, 0xbfb8aa3b, v173
	v_mul_f32_e32 v194, 0xbfb8aa3b, v174
	v_mul_f32_e32 v195, 0xbfb8aa3b, v175
	v_mul_f32_e32 v196, 0xbfb8aa3b, v176
	v_mul_f32_e32 v197, 0xbfb8aa3b, v177
	v_mul_f32_e32 v198, 0xbfb8aa3b, v178
	v_mul_f32_e32 v199, 0xbfb8aa3b, v179
	v_mul_f32_e32 v200, 0xbfb8aa3b, v180
	v_mul_f32_e32 v201, 0xbfb8aa3b, v181
	v_mul_f32_e32 v202, 0xbfb8aa3b, v182
	v_mul_f32_e32 v203, 0xbfb8aa3b, v183
	v_mul_f32_e32 v204, 0xbfb8aa3b, v184
	v_mul_f32_e32 v205, 0xbfb8aa3b, v185
	v_mul_f32_e32 v206, 0xbfb8aa3b, v186
	v_mul_f32_e32 v207, 0xbfb8aa3b, v187
	v_mul_f32_e32 v208, 0xbfb8aa3b, v188
	v_mul_f32_e32 v209, 0xbfb8aa3b, v189
	v_exp_f32_e32 v190, v190
	v_exp_f32_e32 v191, v191
	v_exp_f32_e32 v192, v192
	v_exp_f32_e32 v193, v193
	v_exp_f32_e32 v194, v194
	v_exp_f32_e32 v195, v195
	v_exp_f32_e32 v196, v196
	v_exp_f32_e32 v197, v197
	v_exp_f32_e32 v198, v198
	v_exp_f32_e32 v199, v199
	v_exp_f32_e32 v200, v200
	v_exp_f32_e32 v201, v201
	v_exp_f32_e32 v202, v202
	v_exp_f32_e32 v203, v203
	v_exp_f32_e32 v204, v204
	v_exp_f32_e32 v205, v205
	v_exp_f32_e32 v206, v206
	v_exp_f32_e32 v207, v207
	v_exp_f32_e32 v208, v208
	v_exp_f32_e32 v209, v209
	v_add_f32_e32 v190, 1.0, v190
	v_add_f32_e32 v191, 1.0, v191
	v_add_f32_e32 v192, 1.0, v192
	v_add_f32_e32 v193, 1.0, v193
	v_add_f32_e32 v194, 1.0, v194
	v_add_f32_e32 v195, 1.0, v195
	v_add_f32_e32 v196, 1.0, v196
	v_add_f32_e32 v197, 1.0, v197
	v_add_f32_e32 v198, 1.0, v198
	v_add_f32_e32 v199, 1.0, v199
	v_add_f32_e32 v200, 1.0, v200
	v_add_f32_e32 v201, 1.0, v201
	v_add_f32_e32 v202, 1.0, v202
	v_add_f32_e32 v203, 1.0, v203
	v_add_f32_e32 v204, 1.0, v204
	v_add_f32_e32 v205, 1.0, v205
	v_add_f32_e32 v206, 1.0, v206
	v_add_f32_e32 v207, 1.0, v207
	v_add_f32_e32 v208, 1.0, v208
	v_add_f32_e32 v209, 1.0, v209
	v_rcp_f32_e32 v190, v190
	v_rcp_f32_e32 v191, v191
	v_rcp_f32_e32 v192, v192
	v_rcp_f32_e32 v193, v193
	v_rcp_f32_e32 v194, v194
	v_rcp_f32_e32 v195, v195
	v_rcp_f32_e32 v196, v196
	v_rcp_f32_e32 v197, v197
	v_rcp_f32_e32 v198, v198
	v_rcp_f32_e32 v199, v199
	v_rcp_f32_e32 v200, v200
	v_rcp_f32_e32 v201, v201
	v_rcp_f32_e32 v202, v202
	v_rcp_f32_e32 v203, v203
	v_rcp_f32_e32 v204, v204
	v_rcp_f32_e32 v205, v205
	v_rcp_f32_e32 v206, v206
	v_rcp_f32_e32 v207, v207
	v_rcp_f32_e32 v208, v208
	v_rcp_f32_e32 v209, v209
	v_mul_f32_e32 v170, v170, v190
	v_mul_f32_e32 v171, v171, v191
	v_mul_f32_e32 v172, v172, v192
	v_mul_f32_e32 v173, v173, v193
	v_mul_f32_e32 v174, v174, v194
	v_mul_f32_e32 v175, v175, v195
	v_mul_f32_e32 v176, v176, v196
	v_mul_f32_e32 v177, v177, v197
	v_mul_f32_e32 v178, v178, v198
	v_mul_f32_e32 v179, v179, v199
	v_mul_f32_e32 v180, v180, v200
	v_mul_f32_e32 v181, v181, v201
	v_mul_f32_e32 v182, v182, v202
	v_mul_f32_e32 v183, v183, v203
	v_mul_f32_e32 v184, v184, v204
	v_mul_f32_e32 v185, v185, v205
	v_mul_f32_e32 v186, v186, v206
	v_mul_f32_e32 v187, v187, v207
	v_mul_f32_e32 v188, v188, v208
	v_mul_f32_e32 v189, v189, v209
	ds_write_b32 v58, v170
	ds_write_b32 v58, v171 offset:1024
	ds_write_b32 v58, v172 offset:2048
	ds_write_b32 v58, v173 offset:3072
	ds_write_b32 v58, v174 offset:4096
	ds_write_b32 v58, v175 offset:5120
	ds_write_b32 v58, v176 offset:6144
	ds_write_b32 v58, v177 offset:7168
	ds_write_b32 v58, v178 offset:8192
	ds_write_b32 v58, v179 offset:9216
	ds_write_b32 v58, v180 offset:10240
	ds_write_b32 v58, v181 offset:11264
	ds_write_b32 v58, v182 offset:12288
	ds_write_b32 v58, v183 offset:13312
	ds_write_b32 v58, v184 offset:14336
	ds_write_b32 v58, v185 offset:15360
	ds_write_b32 v58, v186 offset:16384
	ds_write_b32 v58, v187 offset:17408
	ds_write_b32 v58, v188 offset:18432
	ds_write_b32 v58, v189 offset:19456
	s_or_b64 exec, exec, s[4:5]
	s_mov_b32 s3, 0x2aaaaaab
	v_mul_hi_i32 v2, v35, s3
	v_lshrrev_b32_e32 v3, 31, v2
	v_ashrrev_i32_e32 v2, 5, v2
	v_add_u32_e32 v22, v2, v3
	s_movk_i32 s3, 0xc0
	v_mul_lo_u32 v2, v22, s3
	v_sub_u32_e32 v2, v35, v2
	v_readlane_b32 s80, v245, 0
	v_lshlrev_b32_e32 v46, 4, v2
	v_add_u32_e32 v2, 0xbf, v35
	v_readlane_b32 s87, v245, 7
	v_readlane_b32 s86, v245, 6
	v_mov_b32_e32 v4, s31
	v_mov_b32_e32 v3, s87
	v_cmp_gt_u32_e32 vcc, s48, v2
	v_mov_b32_e32 v2, s86
	v_ashrrev_i32_e32 v47, 31, v46
	v_cndmask_b32_e32 v3, v3, v4, vcc
	v_mov_b32_e32 v4, s30
	v_cndmask_b32_e32 v2, v2, v4, vcc
	v_lshl_add_u64 v[2:3], v[2:3], 0, v[40:41]
	v_mov_b32_e32 v6, 0
	v_lshl_add_u64 v[48:49], v[46:47], 2, v[2:3]
	s_mov_b64 s[36:37], 0
	v_mov_b32_e32 v43, v56
	v_mov_b32_e32 v7, v6
	v_mov_b32_e32 v8, v6
	v_mov_b32_e32 v9, v6
	v_mov_b32_e32 v18, v6
	v_mov_b32_e32 v19, v6
	v_mov_b32_e32 v20, v6
	v_mov_b32_e32 v21, v6
	v_mov_b32_e32 v14, v6
	v_mov_b32_e32 v15, v6
	v_mov_b32_e32 v16, v6
	v_mov_b32_e32 v17, v6
	v_mov_b32_e32 v10, v6
	v_mov_b32_e32 v11, v6
	v_mov_b32_e32 v12, v6
	v_mov_b32_e32 v13, v6
	v_mov_b32_e32 v2, v6
	v_mov_b32_e32 v3, v6
	v_mov_b32_e32 v4, v6
	v_mov_b32_e32 v5, v6
	s_waitcnt lgkmcnt(0)
	s_barrier
	v_readlane_b32 s81, v245, 1
	v_readlane_b32 s82, v245, 2
	v_readlane_b32 s83, v245, 3
	v_readlane_b32 s84, v245, 4
	v_readlane_b32 s85, v245, 5
	v_readlane_b32 s88, v245, 8
	v_readlane_b32 s89, v245, 9
	v_readlane_b32 s90, v245, 10
	v_readlane_b32 s91, v245, 11
	v_readlane_b32 s92, v245, 12
	v_readlane_b32 s93, v245, 13
	v_readlane_b32 s94, v245, 14
	v_readlane_b32 s95, v245, 15
	s_mov_b64 s[98:99], 0xc0000
	v_mov_b32_e32 v50, v48
	v_mov_b32_e32 v51, v49
	global_load_dwordx4 v[162:165], v[50:51], off
	v_lshl_add_u64 v[50:51], v[50:51], 0, s[98:99]
	global_load_dwordx4 v[166:169], v[50:51], off
	v_lshl_add_u64 v[50:51], v[50:51], 0, s[98:99]
	global_load_dwordx4 v[170:173], v[50:51], off
	v_lshl_add_u64 v[50:51], v[50:51], 0, s[98:99]
	global_load_dwordx4 v[174:177], v[50:51], off
	v_lshl_add_u64 v[50:51], v[50:51], 0, s[98:99]
	global_load_dwordx4 v[178:181], v[50:51], off
	v_lshl_add_u64 v[50:51], v[50:51], 0, s[98:99]
	global_load_dwordx4 v[182:185], v[50:51], off
	v_lshl_add_u64 v[50:51], v[50:51], 0, s[98:99]
	global_load_dwordx4 v[186:189], v[50:51], off
	v_lshl_add_u64 v[50:51], v[50:51], 0, s[98:99]
	global_load_dwordx4 v[190:193], v[50:51], off
	v_lshl_add_u64 v[50:51], v[50:51], 0, s[98:99]
	global_load_dwordx4 v[194:197], v[50:51], off
	v_lshl_add_u64 v[50:51], v[50:51], 0, s[98:99]
	global_load_dwordx4 v[198:201], v[50:51], off
	v_lshl_add_u64 v[50:51], v[50:51], 0, s[98:99]
	global_load_dwordx4 v[202:205], v[50:51], off
	v_lshl_add_u64 v[50:51], v[50:51], 0, s[98:99]
	global_load_dwordx4 v[206:209], v[50:51], off
	v_lshl_add_u64 v[50:51], v[50:51], 0, s[98:99]
	global_load_dwordx4 v[214:217], v[50:51], off
	v_lshl_add_u64 v[50:51], v[50:51], 0, s[98:99]
	global_load_dwordx4 v[218:221], v[50:51], off
	v_lshl_add_u64 v[50:51], v[50:51], 0, s[98:99]
	global_load_dwordx4 v[222:225], v[50:51], off
	v_lshl_add_u64 v[50:51], v[50:51], 0, s[98:99]
	global_load_dwordx4 v[226:229], v[50:51], off
	ds_read2st64_b32 v[144:145], v43 offset0:0 offset1:1
	ds_read2st64_b32 v[146:147], v43 offset0:16 offset1:17
	ds_read2st64_b32 v[148:149], v43 offset0:32 offset1:33
	ds_read2st64_b32 v[150:151], v43 offset0:48 offset1:49
	ds_read2st64_b32 v[152:153], v43 offset0:64 offset1:65
	ds_read2st64_b32 v[230:231], v43 offset0:2 offset1:3
	ds_read2st64_b32 v[232:233], v43 offset0:18 offset1:19
	ds_read2st64_b32 v[234:235], v43 offset0:34 offset1:35
	ds_read2st64_b32 v[236:237], v43 offset0:50 offset1:51
	ds_read2st64_b32 v[238:239], v43 offset0:66 offset1:67
	s_waitcnt vmcnt(15) lgkmcnt(5)
	v_pk_fma_f32 v[6:7], v[162:163], v[144:145], v[6:7] op_sel_hi:[1,0,1]
	v_pk_fma_f32 v[8:9], v[164:165], v[144:145], v[8:9] op_sel_hi:[1,0,1]
	v_pk_fma_f32 v[18:19], v[162:163], v[146:147], v[18:19] op_sel_hi:[1,0,1]
	v_pk_fma_f32 v[20:21], v[164:165], v[146:147], v[20:21] op_sel_hi:[1,0,1]
	v_pk_fma_f32 v[14:15], v[162:163], v[148:149], v[14:15] op_sel_hi:[1,0,1]
	v_pk_fma_f32 v[16:17], v[164:165], v[148:149], v[16:17] op_sel_hi:[1,0,1]
	v_pk_fma_f32 v[10:11], v[162:163], v[150:151], v[10:11] op_sel_hi:[1,0,1]
	v_pk_fma_f32 v[12:13], v[164:165], v[150:151], v[12:13] op_sel_hi:[1,0,1]
	v_pk_fma_f32 v[2:3], v[162:163], v[152:153], v[2:3] op_sel_hi:[1,0,1]
	v_pk_fma_f32 v[4:5], v[164:165], v[152:153], v[4:5] op_sel_hi:[1,0,1]
	s_waitcnt vmcnt(14)
	v_pk_fma_f32 v[6:7], v[166:167], v[144:145], v[6:7] op_sel:[0,1,0] op_sel_hi:[1,1,1]
	v_pk_fma_f32 v[8:9], v[168:169], v[144:145], v[8:9] op_sel:[0,1,0] op_sel_hi:[1,1,1]
	v_pk_fma_f32 v[18:19], v[166:167], v[146:147], v[18:19] op_sel:[0,1,0] op_sel_hi:[1,1,1]
	v_pk_fma_f32 v[20:21], v[168:169], v[146:147], v[20:21] op_sel:[0,1,0] op_sel_hi:[1,1,1]
	v_pk_fma_f32 v[14:15], v[166:167], v[148:149], v[14:15] op_sel:[0,1,0] op_sel_hi:[1,1,1]
	v_pk_fma_f32 v[16:17], v[168:169], v[148:149], v[16:17] op_sel:[0,1,0] op_sel_hi:[1,1,1]
	v_pk_fma_f32 v[10:11], v[166:167], v[150:151], v[10:11] op_sel:[0,1,0] op_sel_hi:[1,1,1]
	v_pk_fma_f32 v[12:13], v[168:169], v[150:151], v[12:13] op_sel:[0,1,0] op_sel_hi:[1,1,1]
	v_pk_fma_f32 v[2:3], v[166:167], v[152:153], v[2:3] op_sel:[0,1,0] op_sel_hi:[1,1,1]
	v_pk_fma_f32 v[4:5], v[168:169], v[152:153], v[4:5] op_sel:[0,1,0] op_sel_hi:[1,1,1]
	ds_read2st64_b32 v[144:145], v43 offset0:4 offset1:5
	ds_read2st64_b32 v[146:147], v43 offset0:20 offset1:21
	ds_read2st64_b32 v[148:149], v43 offset0:36 offset1:37
	ds_read2st64_b32 v[150:151], v43 offset0:52 offset1:53
	ds_read2st64_b32 v[152:153], v43 offset0:68 offset1:69
	s_waitcnt vmcnt(13) lgkmcnt(5)
	v_pk_fma_f32 v[6:7], v[170:171], v[230:231], v[6:7] op_sel_hi:[1,0,1]
	v_pk_fma_f32 v[8:9], v[172:173], v[230:231], v[8:9] op_sel_hi:[1,0,1]
	v_pk_fma_f32 v[18:19], v[170:171], v[232:233], v[18:19] op_sel_hi:[1,0,1]
	v_pk_fma_f32 v[20:21], v[172:173], v[232:233], v[20:21] op_sel_hi:[1,0,1]
	v_pk_fma_f32 v[14:15], v[170:171], v[234:235], v[14:15] op_sel_hi:[1,0,1]
	v_pk_fma_f32 v[16:17], v[172:173], v[234:235], v[16:17] op_sel_hi:[1,0,1]
	v_pk_fma_f32 v[10:11], v[170:171], v[236:237], v[10:11] op_sel_hi:[1,0,1]
	v_pk_fma_f32 v[12:13], v[172:173], v[236:237], v[12:13] op_sel_hi:[1,0,1]
	v_pk_fma_f32 v[2:3], v[170:171], v[238:239], v[2:3] op_sel_hi:[1,0,1]
	v_pk_fma_f32 v[4:5], v[172:173], v[238:239], v[4:5] op_sel_hi:[1,0,1]
	s_waitcnt vmcnt(12)
	v_pk_fma_f32 v[6:7], v[174:175], v[230:231], v[6:7] op_sel:[0,1,0] op_sel_hi:[1,1,1]
	v_pk_fma_f32 v[8:9], v[176:177], v[230:231], v[8:9] op_sel:[0,1,0] op_sel_hi:[1,1,1]
	v_pk_fma_f32 v[18:19], v[174:175], v[232:233], v[18:19] op_sel:[0,1,0] op_sel_hi:[1,1,1]
	v_pk_fma_f32 v[20:21], v[176:177], v[232:233], v[20:21] op_sel:[0,1,0] op_sel_hi:[1,1,1]
	v_pk_fma_f32 v[14:15], v[174:175], v[234:235], v[14:15] op_sel:[0,1,0] op_sel_hi:[1,1,1]
	v_pk_fma_f32 v[16:17], v[176:177], v[234:235], v[16:17] op_sel:[0,1,0] op_sel_hi:[1,1,1]
	v_pk_fma_f32 v[10:11], v[174:175], v[236:237], v[10:11] op_sel:[0,1,0] op_sel_hi:[1,1,1]
	v_pk_fma_f32 v[12:13], v[176:177], v[236:237], v[12:13] op_sel:[0,1,0] op_sel_hi:[1,1,1]
	v_pk_fma_f32 v[2:3], v[174:175], v[238:239], v[2:3] op_sel:[0,1,0] op_sel_hi:[1,1,1]
	v_pk_fma_f32 v[4:5], v[176:177], v[238:239], v[4:5] op_sel:[0,1,0] op_sel_hi:[1,1,1]
	ds_read2st64_b32 v[230:231], v43 offset0:6 offset1:7
	ds_read2st64_b32 v[232:233], v43 offset0:22 offset1:23
	ds_read2st64_b32 v[234:235], v43 offset0:38 offset1:39
	ds_read2st64_b32 v[236:237], v43 offset0:54 offset1:55
	ds_read2st64_b32 v[238:239], v43 offset0:70 offset1:71
	s_waitcnt vmcnt(11) lgkmcnt(5)
	v_pk_fma_f32 v[6:7], v[178:179], v[144:145], v[6:7] op_sel_hi:[1,0,1]
	v_pk_fma_f32 v[8:9], v[180:181], v[144:145], v[8:9] op_sel_hi:[1,0,1]
	v_pk_fma_f32 v[18:19], v[178:179], v[146:147], v[18:19] op_sel_hi:[1,0,1]
	v_pk_fma_f32 v[20:21], v[180:181], v[146:147], v[20:21] op_sel_hi:[1,0,1]
	v_pk_fma_f32 v[14:15], v[178:179], v[148:149], v[14:15] op_sel_hi:[1,0,1]
	v_pk_fma_f32 v[16:17], v[180:181], v[148:149], v[16:17] op_sel_hi:[1,0,1]
	v_pk_fma_f32 v[10:11], v[178:179], v[150:151], v[10:11] op_sel_hi:[1,0,1]
	v_pk_fma_f32 v[12:13], v[180:181], v[150:151], v[12:13] op_sel_hi:[1,0,1]
	v_pk_fma_f32 v[2:3], v[178:179], v[152:153], v[2:3] op_sel_hi:[1,0,1]
	v_pk_fma_f32 v[4:5], v[180:181], v[152:153], v[4:5] op_sel_hi:[1,0,1]
	s_waitcnt vmcnt(10)
	v_pk_fma_f32 v[6:7], v[182:183], v[144:145], v[6:7] op_sel:[0,1,0] op_sel_hi:[1,1,1]
	v_pk_fma_f32 v[8:9], v[184:185], v[144:145], v[8:9] op_sel:[0,1,0] op_sel_hi:[1,1,1]
	v_pk_fma_f32 v[18:19], v[182:183], v[146:147], v[18:19] op_sel:[0,1,0] op_sel_hi:[1,1,1]
	v_pk_fma_f32 v[20:21], v[184:185], v[146:147], v[20:21] op_sel:[0,1,0] op_sel_hi:[1,1,1]
	v_pk_fma_f32 v[14:15], v[182:183], v[148:149], v[14:15] op_sel:[0,1,0] op_sel_hi:[1,1,1]
	v_pk_fma_f32 v[16:17], v[184:185], v[148:149], v[16:17] op_sel:[0,1,0] op_sel_hi:[1,1,1]
	v_pk_fma_f32 v[10:11], v[182:183], v[150:151], v[10:11] op_sel:[0,1,0] op_sel_hi:[1,1,1]
	v_pk_fma_f32 v[12:13], v[184:185], v[150:151], v[12:13] op_sel:[0,1,0] op_sel_hi:[1,1,1]
	v_pk_fma_f32 v[2:3], v[182:183], v[152:153], v[2:3] op_sel:[0,1,0] op_sel_hi:[1,1,1]
	v_pk_fma_f32 v[4:5], v[184:185], v[152:153], v[4:5] op_sel:[0,1,0] op_sel_hi:[1,1,1]
	ds_read2st64_b32 v[144:145], v43 offset0:8 offset1:9
	ds_read2st64_b32 v[146:147], v43 offset0:24 offset1:25
	ds_read2st64_b32 v[148:149], v43 offset0:40 offset1:41
	ds_read2st64_b32 v[150:151], v43 offset0:56 offset1:57
	ds_read2st64_b32 v[152:153], v43 offset0:72 offset1:73
	s_waitcnt vmcnt(9) lgkmcnt(5)
	v_pk_fma_f32 v[6:7], v[186:187], v[230:231], v[6:7] op_sel_hi:[1,0,1]
	v_pk_fma_f32 v[8:9], v[188:189], v[230:231], v[8:9] op_sel_hi:[1,0,1]
	v_pk_fma_f32 v[18:19], v[186:187], v[232:233], v[18:19] op_sel_hi:[1,0,1]
	v_pk_fma_f32 v[20:21], v[188:189], v[232:233], v[20:21] op_sel_hi:[1,0,1]
	v_pk_fma_f32 v[14:15], v[186:187], v[234:235], v[14:15] op_sel_hi:[1,0,1]
	v_pk_fma_f32 v[16:17], v[188:189], v[234:235], v[16:17] op_sel_hi:[1,0,1]
	v_pk_fma_f32 v[10:11], v[186:187], v[236:237], v[10:11] op_sel_hi:[1,0,1]
	v_pk_fma_f32 v[12:13], v[188:189], v[236:237], v[12:13] op_sel_hi:[1,0,1]
	v_pk_fma_f32 v[2:3], v[186:187], v[238:239], v[2:3] op_sel_hi:[1,0,1]
	v_pk_fma_f32 v[4:5], v[188:189], v[238:239], v[4:5] op_sel_hi:[1,0,1]
	s_waitcnt vmcnt(8)
	v_pk_fma_f32 v[6:7], v[190:191], v[230:231], v[6:7] op_sel:[0,1,0] op_sel_hi:[1,1,1]
	v_pk_fma_f32 v[8:9], v[192:193], v[230:231], v[8:9] op_sel:[0,1,0] op_sel_hi:[1,1,1]
	v_pk_fma_f32 v[18:19], v[190:191], v[232:233], v[18:19] op_sel:[0,1,0] op_sel_hi:[1,1,1]
	v_pk_fma_f32 v[20:21], v[192:193], v[232:233], v[20:21] op_sel:[0,1,0] op_sel_hi:[1,1,1]
	v_pk_fma_f32 v[14:15], v[190:191], v[234:235], v[14:15] op_sel:[0,1,0] op_sel_hi:[1,1,1]
	v_pk_fma_f32 v[16:17], v[192:193], v[234:235], v[16:17] op_sel:[0,1,0] op_sel_hi:[1,1,1]
	v_pk_fma_f32 v[10:11], v[190:191], v[236:237], v[10:11] op_sel:[0,1,0] op_sel_hi:[1,1,1]
	v_pk_fma_f32 v[12:13], v[192:193], v[236:237], v[12:13] op_sel:[0,1,0] op_sel_hi:[1,1,1]
	v_pk_fma_f32 v[2:3], v[190:191], v[238:239], v[2:3] op_sel:[0,1,0] op_sel_hi:[1,1,1]
	v_pk_fma_f32 v[4:5], v[192:193], v[238:239], v[4:5] op_sel:[0,1,0] op_sel_hi:[1,1,1]
	ds_read2st64_b32 v[230:231], v43 offset0:10 offset1:11
	ds_read2st64_b32 v[232:233], v43 offset0:26 offset1:27
	ds_read2st64_b32 v[234:235], v43 offset0:42 offset1:43
	ds_read2st64_b32 v[236:237], v43 offset0:58 offset1:59
	ds_read2st64_b32 v[238:239], v43 offset0:74 offset1:75
	s_waitcnt vmcnt(7) lgkmcnt(5)
	v_pk_fma_f32 v[6:7], v[194:195], v[144:145], v[6:7] op_sel_hi:[1,0,1]
	v_pk_fma_f32 v[8:9], v[196:197], v[144:145], v[8:9] op_sel_hi:[1,0,1]
	v_pk_fma_f32 v[18:19], v[194:195], v[146:147], v[18:19] op_sel_hi:[1,0,1]
	v_pk_fma_f32 v[20:21], v[196:197], v[146:147], v[20:21] op_sel_hi:[1,0,1]
	v_pk_fma_f32 v[14:15], v[194:195], v[148:149], v[14:15] op_sel_hi:[1,0,1]
	v_pk_fma_f32 v[16:17], v[196:197], v[148:149], v[16:17] op_sel_hi:[1,0,1]
	v_pk_fma_f32 v[10:11], v[194:195], v[150:151], v[10:11] op_sel_hi:[1,0,1]
	v_pk_fma_f32 v[12:13], v[196:197], v[150:151], v[12:13] op_sel_hi:[1,0,1]
	v_pk_fma_f32 v[2:3], v[194:195], v[152:153], v[2:3] op_sel_hi:[1,0,1]
	v_pk_fma_f32 v[4:5], v[196:197], v[152:153], v[4:5] op_sel_hi:[1,0,1]
	s_waitcnt vmcnt(6)
	v_pk_fma_f32 v[6:7], v[198:199], v[144:145], v[6:7] op_sel:[0,1,0] op_sel_hi:[1,1,1]
	v_pk_fma_f32 v[8:9], v[200:201], v[144:145], v[8:9] op_sel:[0,1,0] op_sel_hi:[1,1,1]
	v_pk_fma_f32 v[18:19], v[198:199], v[146:147], v[18:19] op_sel:[0,1,0] op_sel_hi:[1,1,1]
	v_pk_fma_f32 v[20:21], v[200:201], v[146:147], v[20:21] op_sel:[0,1,0] op_sel_hi:[1,1,1]
	v_pk_fma_f32 v[14:15], v[198:199], v[148:149], v[14:15] op_sel:[0,1,0] op_sel_hi:[1,1,1]
	v_pk_fma_f32 v[16:17], v[200:201], v[148:149], v[16:17] op_sel:[0,1,0] op_sel_hi:[1,1,1]
	v_pk_fma_f32 v[10:11], v[198:199], v[150:151], v[10:11] op_sel:[0,1,0] op_sel_hi:[1,1,1]
	v_pk_fma_f32 v[12:13], v[200:201], v[150:151], v[12:13] op_sel:[0,1,0] op_sel_hi:[1,1,1]
	v_pk_fma_f32 v[2:3], v[198:199], v[152:153], v[2:3] op_sel:[0,1,0] op_sel_hi:[1,1,1]
	v_pk_fma_f32 v[4:5], v[200:201], v[152:153], v[4:5] op_sel:[0,1,0] op_sel_hi:[1,1,1]
	ds_read2st64_b32 v[144:145], v43 offset0:12 offset1:13
	ds_read2st64_b32 v[146:147], v43 offset0:28 offset1:29
	ds_read2st64_b32 v[148:149], v43 offset0:44 offset1:45
	ds_read2st64_b32 v[150:151], v43 offset0:60 offset1:61
	ds_read2st64_b32 v[152:153], v43 offset0:76 offset1:77
	s_waitcnt vmcnt(5) lgkmcnt(5)
	v_pk_fma_f32 v[6:7], v[202:203], v[230:231], v[6:7] op_sel_hi:[1,0,1]
	v_pk_fma_f32 v[8:9], v[204:205], v[230:231], v[8:9] op_sel_hi:[1,0,1]
	v_pk_fma_f32 v[18:19], v[202:203], v[232:233], v[18:19] op_sel_hi:[1,0,1]
	v_pk_fma_f32 v[20:21], v[204:205], v[232:233], v[20:21] op_sel_hi:[1,0,1]
	v_pk_fma_f32 v[14:15], v[202:203], v[234:235], v[14:15] op_sel_hi:[1,0,1]
	v_pk_fma_f32 v[16:17], v[204:205], v[234:235], v[16:17] op_sel_hi:[1,0,1]
	v_pk_fma_f32 v[10:11], v[202:203], v[236:237], v[10:11] op_sel_hi:[1,0,1]
	v_pk_fma_f32 v[12:13], v[204:205], v[236:237], v[12:13] op_sel_hi:[1,0,1]
	v_pk_fma_f32 v[2:3], v[202:203], v[238:239], v[2:3] op_sel_hi:[1,0,1]
	v_pk_fma_f32 v[4:5], v[204:205], v[238:239], v[4:5] op_sel_hi:[1,0,1]
	s_waitcnt vmcnt(4)
	v_pk_fma_f32 v[6:7], v[206:207], v[230:231], v[6:7] op_sel:[0,1,0] op_sel_hi:[1,1,1]
	v_pk_fma_f32 v[8:9], v[208:209], v[230:231], v[8:9] op_sel:[0,1,0] op_sel_hi:[1,1,1]
	v_pk_fma_f32 v[18:19], v[206:207], v[232:233], v[18:19] op_sel:[0,1,0] op_sel_hi:[1,1,1]
	v_pk_fma_f32 v[20:21], v[208:209], v[232:233], v[20:21] op_sel:[0,1,0] op_sel_hi:[1,1,1]
	v_pk_fma_f32 v[14:15], v[206:207], v[234:235], v[14:15] op_sel:[0,1,0] op_sel_hi:[1,1,1]
	v_pk_fma_f32 v[16:17], v[208:209], v[234:235], v[16:17] op_sel:[0,1,0] op_sel_hi:[1,1,1]
	v_pk_fma_f32 v[10:11], v[206:207], v[236:237], v[10:11] op_sel:[0,1,0] op_sel_hi:[1,1,1]
	v_pk_fma_f32 v[12:13], v[208:209], v[236:237], v[12:13] op_sel:[0,1,0] op_sel_hi:[1,1,1]
	v_pk_fma_f32 v[2:3], v[206:207], v[238:239], v[2:3] op_sel:[0,1,0] op_sel_hi:[1,1,1]
	v_pk_fma_f32 v[4:5], v[208:209], v[238:239], v[4:5] op_sel:[0,1,0] op_sel_hi:[1,1,1]
	ds_read2st64_b32 v[230:231], v43 offset0:14 offset1:15
	ds_read2st64_b32 v[232:233], v43 offset0:30 offset1:31
	ds_read2st64_b32 v[234:235], v43 offset0:46 offset1:47
	ds_read2st64_b32 v[236:237], v43 offset0:62 offset1:63
	ds_read2st64_b32 v[238:239], v43 offset0:78 offset1:79
	s_waitcnt vmcnt(3) lgkmcnt(5)
	v_pk_fma_f32 v[6:7], v[214:215], v[144:145], v[6:7] op_sel_hi:[1,0,1]
	v_pk_fma_f32 v[8:9], v[216:217], v[144:145], v[8:9] op_sel_hi:[1,0,1]
	v_pk_fma_f32 v[18:19], v[214:215], v[146:147], v[18:19] op_sel_hi:[1,0,1]
	v_pk_fma_f32 v[20:21], v[216:217], v[146:147], v[20:21] op_sel_hi:[1,0,1]
	v_pk_fma_f32 v[14:15], v[214:215], v[148:149], v[14:15] op_sel_hi:[1,0,1]
	v_pk_fma_f32 v[16:17], v[216:217], v[148:149], v[16:17] op_sel_hi:[1,0,1]
	v_pk_fma_f32 v[10:11], v[214:215], v[150:151], v[10:11] op_sel_hi:[1,0,1]
	v_pk_fma_f32 v[12:13], v[216:217], v[150:151], v[12:13] op_sel_hi:[1,0,1]
	v_pk_fma_f32 v[2:3], v[214:215], v[152:153], v[2:3] op_sel_hi:[1,0,1]
	v_pk_fma_f32 v[4:5], v[216:217], v[152:153], v[4:5] op_sel_hi:[1,0,1]
	s_waitcnt vmcnt(2)
	v_pk_fma_f32 v[6:7], v[218:219], v[144:145], v[6:7] op_sel:[0,1,0] op_sel_hi:[1,1,1]
	v_pk_fma_f32 v[8:9], v[220:221], v[144:145], v[8:9] op_sel:[0,1,0] op_sel_hi:[1,1,1]
	v_pk_fma_f32 v[18:19], v[218:219], v[146:147], v[18:19] op_sel:[0,1,0] op_sel_hi:[1,1,1]
	v_pk_fma_f32 v[20:21], v[220:221], v[146:147], v[20:21] op_sel:[0,1,0] op_sel_hi:[1,1,1]
	v_pk_fma_f32 v[14:15], v[218:219], v[148:149], v[14:15] op_sel:[0,1,0] op_sel_hi:[1,1,1]
	v_pk_fma_f32 v[16:17], v[220:221], v[148:149], v[16:17] op_sel:[0,1,0] op_sel_hi:[1,1,1]
	v_pk_fma_f32 v[10:11], v[218:219], v[150:151], v[10:11] op_sel:[0,1,0] op_sel_hi:[1,1,1]
	v_pk_fma_f32 v[12:13], v[220:221], v[150:151], v[12:13] op_sel:[0,1,0] op_sel_hi:[1,1,1]
	v_pk_fma_f32 v[2:3], v[218:219], v[152:153], v[2:3] op_sel:[0,1,0] op_sel_hi:[1,1,1]
	v_pk_fma_f32 v[4:5], v[220:221], v[152:153], v[4:5] op_sel:[0,1,0] op_sel_hi:[1,1,1]
	s_waitcnt vmcnt(1) lgkmcnt(0)
	v_pk_fma_f32 v[6:7], v[222:223], v[230:231], v[6:7] op_sel_hi:[1,0,1]
	v_pk_fma_f32 v[8:9], v[224:225], v[230:231], v[8:9] op_sel_hi:[1,0,1]
	v_pk_fma_f32 v[18:19], v[222:223], v[232:233], v[18:19] op_sel_hi:[1,0,1]
	v_pk_fma_f32 v[20:21], v[224:225], v[232:233], v[20:21] op_sel_hi:[1,0,1]
	v_pk_fma_f32 v[14:15], v[222:223], v[234:235], v[14:15] op_sel_hi:[1,0,1]
	v_pk_fma_f32 v[16:17], v[224:225], v[234:235], v[16:17] op_sel_hi:[1,0,1]
	v_pk_fma_f32 v[10:11], v[222:223], v[236:237], v[10:11] op_sel_hi:[1,0,1]
	v_pk_fma_f32 v[12:13], v[224:225], v[236:237], v[12:13] op_sel_hi:[1,0,1]
	v_pk_fma_f32 v[2:3], v[222:223], v[238:239], v[2:3] op_sel_hi:[1,0,1]
	v_pk_fma_f32 v[4:5], v[224:225], v[238:239], v[4:5] op_sel_hi:[1,0,1]
	s_waitcnt vmcnt(0)
	v_pk_fma_f32 v[6:7], v[226:227], v[230:231], v[6:7] op_sel:[0,1,0] op_sel_hi:[1,1,1]
	v_pk_fma_f32 v[8:9], v[228:229], v[230:231], v[8:9] op_sel:[0,1,0] op_sel_hi:[1,1,1]
	v_pk_fma_f32 v[18:19], v[226:227], v[232:233], v[18:19] op_sel:[0,1,0] op_sel_hi:[1,1,1]
	v_pk_fma_f32 v[20:21], v[228:229], v[232:233], v[20:21] op_sel:[0,1,0] op_sel_hi:[1,1,1]
	v_pk_fma_f32 v[14:15], v[226:227], v[234:235], v[14:15] op_sel:[0,1,0] op_sel_hi:[1,1,1]
	v_pk_fma_f32 v[16:17], v[228:229], v[234:235], v[16:17] op_sel:[0,1,0] op_sel_hi:[1,1,1]
	v_pk_fma_f32 v[10:11], v[226:227], v[236:237], v[10:11] op_sel:[0,1,0] op_sel_hi:[1,1,1]
	v_pk_fma_f32 v[12:13], v[228:229], v[236:237], v[12:13] op_sel:[0,1,0] op_sel_hi:[1,1,1]
	v_pk_fma_f32 v[2:3], v[226:227], v[238:239], v[2:3] op_sel:[0,1,0] op_sel_hi:[1,1,1]
	v_pk_fma_f32 v[4:5], v[228:229], v[238:239], v[4:5] op_sel:[0,1,0] op_sel_hi:[1,1,1]
	ds_write_b128 v66, v[6:9] offset:20480
	ds_write_b128 v66, v[18:21] offset:20496
	ds_write_b128 v66, v[14:17] offset:20512
	ds_write_b128 v66, v[10:13] offset:20528
	ds_write_b128 v66, v[2:5] offset:20544
	s_waitcnt lgkmcnt(0)
	s_barrier
	s_and_saveexec_b64 s[4:5], s[68:69]
	s_cbranch_execz .LBB0_8
	v_readlane_b32 s80, v245, 0
	v_readlane_b32 s16, v245, 16
	v_readlane_b32 s89, v245, 9
	v_readlane_b32 s17, v245, 17
	v_readlane_b32 s88, v245, 8
	v_mov_b32_e32 v2, s89
	v_mov_b32_e32 v3, s17
	v_cndmask_b32_e32 v5, v2, v3, vcc
	v_mov_b32_e32 v2, s88
	v_mov_b32_e32 v3, s16
	v_cndmask_b32_e32 v4, v2, v3, vcc
	v_or_b32_e32 v2, v46, v60
	v_ashrrev_i32_e32 v3, 31, v2
	v_lshl_add_u64 v[4:5], v[2:3], 2, v[4:5]
	global_load_dword v3, v[4:5], off
	v_add_u32_e32 v4, v61, v62
	ds_read_b32 v4, v4 offset:20480
	s_movk_i32 s3, 0xc00
	v_readlane_b32 s81, v245, 1
	v_readlane_b32 s82, v245, 2
	v_readlane_b32 s83, v245, 3
	v_readlane_b32 s84, v245, 4
	v_readlane_b32 s85, v245, 5
	v_readlane_b32 s86, v245, 6
	v_readlane_b32 s87, v245, 7
	v_readlane_b32 s90, v245, 10
	v_readlane_b32 s91, v245, 11
	v_readlane_b32 s92, v245, 12
	v_readlane_b32 s93, v245, 13
	v_readlane_b32 s94, v245, 14
	v_readlane_b32 s95, v245, 15
	v_readlane_b32 s18, v245, 18
	v_readlane_b32 s19, v245, 19
	v_readlane_b32 s20, v245, 20
	v_readlane_b32 s21, v245, 21
	v_readlane_b32 s22, v245, 22
	v_readlane_b32 s23, v245, 23
	v_readlane_b32 s24, v245, 24
	v_readlane_b32 s25, v245, 25
	v_readlane_b32 s26, v245, 26
	v_readlane_b32 s27, v245, 27
	v_readlane_b32 s28, v245, 28
	v_readlane_b32 s29, v245, 29
	v_readlane_b32 s30, v245, 30
	v_readlane_b32 s31, v245, 31
	s_waitcnt vmcnt(0) lgkmcnt(0)
	v_add_f32_e32 v3, v3, v4
	ds_read_b32 v4, v67 offset:20480
	s_waitcnt lgkmcnt(0)
	v_add_f32_e32 v3, v3, v4
	ds_read_b32 v4, v68 offset:20480
	s_waitcnt lgkmcnt(0)
	v_add_f32_e32 v3, v3, v4
	ds_read_b32 v4, v69 offset:20480
	s_waitcnt lgkmcnt(0)
	v_add_f32_e32 v3, v3, v4
	ds_read_b32 v4, v70 offset:20480
	s_waitcnt lgkmcnt(0)
	v_add_f32_e32 v3, v3, v4
	ds_read_b32 v4, v71 offset:20480
	s_waitcnt lgkmcnt(0)
	v_add_f32_e32 v3, v3, v4
	ds_read_b32 v4, v72 offset:20480
	s_waitcnt lgkmcnt(0)
	v_add_f32_e32 v3, v3, v4
	ds_read_b32 v4, v73 offset:20480
	s_waitcnt lgkmcnt(0)
	v_add_f32_e32 v3, v3, v4
	ds_read_b32 v4, v74 offset:20480
	s_waitcnt lgkmcnt(0)
	v_add_f32_e32 v3, v3, v4
	ds_read_b32 v4, v75 offset:20480
	s_waitcnt lgkmcnt(0)
	v_add_f32_e32 v3, v3, v4
	ds_read_b32 v4, v76 offset:20480
	s_waitcnt lgkmcnt(0)
	v_add_f32_e32 v3, v3, v4
	ds_read_b32 v4, v77 offset:20480
	s_waitcnt lgkmcnt(0)
	v_add_f32_e32 v3, v3, v4
	ds_read_b32 v4, v78 offset:20480
	s_waitcnt lgkmcnt(0)
	v_add_f32_e32 v3, v3, v4
	ds_read_b32 v4, v79 offset:20480
	s_waitcnt lgkmcnt(0)
	v_add_f32_e32 v3, v3, v4
	ds_read_b32 v4, v80 offset:20480
	s_waitcnt lgkmcnt(0)
	v_add_f32_e32 v3, v3, v4
	ds_read_b32 v4, v81 offset:20480
	s_waitcnt lgkmcnt(0)
	v_add_f32_e32 v3, v3, v4
	ds_read_b32 v4, v82 offset:20480
	s_waitcnt lgkmcnt(0)
	v_add_f32_e32 v3, v3, v4
	ds_read_b32 v4, v83 offset:20480
	s_waitcnt lgkmcnt(0)
	v_add_f32_e32 v3, v3, v4
	ds_read_b32 v4, v84 offset:20480
	s_waitcnt lgkmcnt(0)
	v_add_f32_e32 v3, v3, v4
	ds_read_b32 v4, v85 offset:20480
	s_waitcnt lgkmcnt(0)
	v_add_f32_e32 v3, v3, v4
	ds_read_b32 v4, v86 offset:20480
	s_waitcnt lgkmcnt(0)
	v_add_f32_e32 v3, v3, v4
	ds_read_b32 v4, v87 offset:20480
	s_waitcnt lgkmcnt(0)
	v_add_f32_e32 v3, v3, v4
	ds_read_b32 v4, v88 offset:20480
	s_waitcnt lgkmcnt(0)
	v_add_f32_e32 v3, v3, v4
	ds_read_b32 v4, v89 offset:20480
	s_waitcnt lgkmcnt(0)
	v_add_f32_e32 v3, v3, v4
	ds_read_b32 v4, v90 offset:20480
	s_waitcnt lgkmcnt(0)
	v_add_f32_e32 v3, v3, v4
	ds_read_b32 v4, v91 offset:20480
	s_waitcnt lgkmcnt(0)
	v_add_f32_e32 v3, v3, v4
	ds_read_b32 v4, v92 offset:20480
	s_waitcnt lgkmcnt(0)
	v_add_f32_e32 v3, v3, v4
	ds_read_b32 v4, v93 offset:20480
	s_waitcnt lgkmcnt(0)
	v_add_f32_e32 v3, v3, v4
	ds_read_b32 v4, v94 offset:20480
	s_waitcnt lgkmcnt(0)
	v_add_f32_e32 v3, v3, v4
	ds_read_b32 v4, v95 offset:20480
	s_waitcnt lgkmcnt(0)
	v_add_f32_e32 v3, v3, v4
	ds_read_b32 v4, v96 offset:20480
	s_waitcnt lgkmcnt(0)
	v_add_f32_e32 v3, v3, v4
	ds_read_b32 v4, v97 offset:20480
	s_waitcnt lgkmcnt(0)
	v_add_f32_e32 v3, v3, v4
	ds_read_b32 v4, v98 offset:20480
	s_waitcnt lgkmcnt(0)
	v_add_f32_e32 v3, v3, v4
	ds_read_b32 v4, v99 offset:20480
	s_waitcnt lgkmcnt(0)
	v_add_f32_e32 v3, v3, v4
	ds_read_b32 v4, v100 offset:20480
	s_waitcnt lgkmcnt(0)
	v_add_f32_e32 v3, v3, v4
	ds_read_b32 v4, v101 offset:20480
	s_waitcnt lgkmcnt(0)
	v_add_f32_e32 v3, v3, v4
	ds_read_b32 v4, v102 offset:20480
	s_waitcnt lgkmcnt(0)
	v_add_f32_e32 v3, v3, v4
	ds_read_b32 v4, v103 offset:20480
	s_waitcnt lgkmcnt(0)
	v_add_f32_e32 v3, v3, v4
	ds_read_b32 v4, v104 offset:20480
	s_waitcnt lgkmcnt(0)
	v_add_f32_e32 v3, v3, v4
	ds_read_b32 v4, v105 offset:20480
	s_waitcnt lgkmcnt(0)
	v_add_f32_e32 v3, v3, v4
	ds_read_b32 v4, v106 offset:20480
	s_waitcnt lgkmcnt(0)
	v_add_f32_e32 v3, v3, v4
	ds_read_b32 v4, v107 offset:20480
	s_waitcnt lgkmcnt(0)
	v_add_f32_e32 v3, v3, v4
	ds_read_b32 v4, v108 offset:20480
	s_waitcnt lgkmcnt(0)
	v_add_f32_e32 v3, v3, v4
	ds_read_b32 v4, v109 offset:20480
	s_waitcnt lgkmcnt(0)
	v_add_f32_e32 v3, v3, v4
	ds_read_b32 v4, v110 offset:20480
	s_waitcnt lgkmcnt(0)
	v_add_f32_e32 v3, v3, v4
	ds_read_b32 v4, v111 offset:20480
	s_waitcnt lgkmcnt(0)
	v_add_f32_e32 v3, v3, v4
	ds_read_b32 v4, v112 offset:20480
	s_waitcnt lgkmcnt(0)
	v_add_f32_e32 v3, v3, v4
	ds_read_b32 v4, v113 offset:20480
	s_waitcnt lgkmcnt(0)
	v_add_f32_e32 v3, v3, v4
	ds_read_b32 v4, v114 offset:20480
	s_waitcnt lgkmcnt(0)
	v_add_f32_e32 v3, v3, v4
	ds_read_b32 v4, v115 offset:20480
	s_waitcnt lgkmcnt(0)
	v_add_f32_e32 v3, v3, v4
	ds_read_b32 v4, v116 offset:20480
	s_waitcnt lgkmcnt(0)
	v_add_f32_e32 v3, v3, v4
	ds_read_b32 v4, v117 offset:20480
	s_waitcnt lgkmcnt(0)
	v_add_f32_e32 v3, v3, v4
	ds_read_b32 v4, v118 offset:20480
	s_waitcnt lgkmcnt(0)
	v_add_f32_e32 v3, v3, v4
	ds_read_b32 v4, v119 offset:20480
	s_waitcnt lgkmcnt(0)
	v_add_f32_e32 v3, v3, v4
	ds_read_b32 v4, v120 offset:20480
	s_waitcnt lgkmcnt(0)
	v_add_f32_e32 v3, v3, v4
	ds_read_b32 v4, v121 offset:20480
	s_waitcnt lgkmcnt(0)
	v_add_f32_e32 v3, v3, v4
	ds_read_b32 v4, v122 offset:20480
	s_waitcnt lgkmcnt(0)
	v_add_f32_e32 v3, v3, v4
	ds_read_b32 v4, v123 offset:20480
	s_waitcnt lgkmcnt(0)
	v_add_f32_e32 v3, v3, v4
	ds_read_b32 v4, v124 offset:20480
	s_waitcnt lgkmcnt(0)
	v_add_f32_e32 v3, v3, v4
	ds_read_b32 v4, v125 offset:20480
	s_waitcnt lgkmcnt(0)
	v_add_f32_e32 v3, v3, v4
	ds_read_b32 v4, v126 offset:20480
	s_waitcnt lgkmcnt(0)
	v_add_f32_e32 v3, v3, v4
	ds_read_b32 v4, v127 offset:20480
	s_waitcnt lgkmcnt(0)
	v_add_f32_e32 v3, v3, v4
	ds_read_b32 v4, v128 offset:20480
	s_waitcnt lgkmcnt(0)
	v_add_f32_e32 v3, v3, v4
	ds_read_b32 v4, v129 offset:20480
	s_waitcnt lgkmcnt(0)
	v_add_f32_e32 v6, v3, v4
	v_mad_u64_u32 v[4:5], s[36:37], v22, 5, v[34:35]
	v_mad_u64_u32 v[2:3], s[36:37], v4, s3, v[2:3]
	v_ashrrev_i32_e32 v3, 31, v2
	v_lshl_add_u64 v[2:3], v[2:3], 2, s[96:97]
	global_store_dword v[2:3], v6, off
	s_branch .LBB0_8
